# adaLN GEMV row loop rewritten by hand: one silu per lane (same exp + IEEE divide sequence) broadcast with v_readlane, 32 weight rows in flight with counted vmcnt, same fma order
# speedup vs baseline: 1.0057x; 1.0057x over previous
; #define GAS __attribute__((address_space(1)))
; #define ARG(k) (ldarg<k>())
; __device__ __forceinline__ float silu_f(float v) { return v / (1.f + __expf(-v)); }
; __device__ __forceinline__ void p0_prologue(Frame& F) {
;     ...
;         for (int it = F.vcu * 3 + (F.wave - 5); it < 2 * 24 * ADA_KS; it += F.G * 3) {
;             const int l = it / (24 * ADA_KS), rem = it % (24 * ADA_KS), cg = rem / ADA_KS, ks = rem % ADA_KS;
;             const float* W = ARG(4) + (size_t)l * DM * 6144 + cg * 256 + 4 * F.lane;
;             f32x4 a0 = {0.f, 0.f, 0.f, 0.f}, a1 = a0, a2 = a0;
;             const int kbeg = ks * (DM / ADA_KS);
; #pragma unroll 8
;             for (int k = kbeg; k < kbeg + DM / ADA_KS; ++k) {
;                 const f32x4 w = *(const GAS f32x4*)(W + (size_t)k * 6144);
;                 const float s0 = silu_f(c[k]), s1 = silu_f(c[DM + k]), s2 = silu_f(cctx[k]);
;                 a0 += w * s0; a1 += w * s1; a2 += w * s2;
;             }
.LBB0_1196:
	s_mov_b32 s4, 0xfffd6000
	s_mov_b32 s5, -1
	v_lshl_add_u64 v[60:61], v[56:57], 0, s[4:5]
	s_mov_b64 s[6:7], 0x6000
	v_lshrrev_b32_e32 v5, 2, v54
	v_add_u32_e32 v6, v5, v189
	s_mov_b32 s16, s73
	s_mov_b32 s17, s74
	s_mov_b32 s18, s71
	s_mov_b32 s19, s72
	global_load_dword v2, v5, s[16:17]
	global_load_dword v3, v6, s[16:17]
	global_load_dword v4, v5, s[18:19]
	global_load_dwordx4 v[64:67], v[60:61], off nt
	v_lshl_add_u64 v[60:61], v[60:61], 0, s[6:7]
	global_load_dwordx4 v[68:71], v[60:61], off nt
	v_lshl_add_u64 v[60:61], v[60:61], 0, s[6:7]
	global_load_dwordx4 v[72:75], v[60:61], off nt
	v_lshl_add_u64 v[60:61], v[60:61], 0, s[6:7]
	global_load_dwordx4 v[76:79], v[60:61], off nt
	v_lshl_add_u64 v[60:61], v[60:61], 0, s[6:7]
	global_load_dwordx4 v[80:83], v[60:61], off nt
	v_lshl_add_u64 v[60:61], v[60:61], 0, s[6:7]
	global_load_dwordx4 v[84:87], v[60:61], off nt
	v_lshl_add_u64 v[60:61], v[60:61], 0, s[6:7]
	global_load_dwordx4 v[88:91], v[60:61], off nt
	v_lshl_add_u64 v[60:61], v[60:61], 0, s[6:7]
	global_load_dwordx4 v[92:95], v[60:61], off nt
	v_lshl_add_u64 v[60:61], v[60:61], 0, s[6:7]
	global_load_dwordx4 v[96:99], v[60:61], off nt
	v_lshl_add_u64 v[60:61], v[60:61], 0, s[6:7]
	global_load_dwordx4 v[100:103], v[60:61], off nt
	v_lshl_add_u64 v[60:61], v[60:61], 0, s[6:7]
	global_load_dwordx4 v[104:107], v[60:61], off nt
	v_lshl_add_u64 v[60:61], v[60:61], 0, s[6:7]
	global_load_dwordx4 v[108:111], v[60:61], off nt
	v_lshl_add_u64 v[60:61], v[60:61], 0, s[6:7]
	global_load_dwordx4 v[112:115], v[60:61], off nt
	v_lshl_add_u64 v[60:61], v[60:61], 0, s[6:7]
	global_load_dwordx4 v[116:119], v[60:61], off nt
	v_lshl_add_u64 v[60:61], v[60:61], 0, s[6:7]
	global_load_dwordx4 v[120:123], v[60:61], off nt
	v_lshl_add_u64 v[60:61], v[60:61], 0, s[6:7]
	global_load_dwordx4 v[124:127], v[60:61], off nt
	v_lshl_add_u64 v[60:61], v[60:61], 0, s[6:7]
	global_load_dwordx4 v[128:131], v[60:61], off nt
	v_lshl_add_u64 v[60:61], v[60:61], 0, s[6:7]
	global_load_dwordx4 v[132:135], v[60:61], off nt
	v_lshl_add_u64 v[60:61], v[60:61], 0, s[6:7]
	global_load_dwordx4 v[136:139], v[60:61], off nt
	v_lshl_add_u64 v[60:61], v[60:61], 0, s[6:7]
	global_load_dwordx4 v[140:143], v[60:61], off nt
	v_lshl_add_u64 v[60:61], v[60:61], 0, s[6:7]
	global_load_dwordx4 v[144:147], v[60:61], off nt
	v_lshl_add_u64 v[60:61], v[60:61], 0, s[6:7]
	global_load_dwordx4 v[148:151], v[60:61], off nt
	v_lshl_add_u64 v[60:61], v[60:61], 0, s[6:7]
	global_load_dwordx4 v[152:155], v[60:61], off nt
	v_lshl_add_u64 v[60:61], v[60:61], 0, s[6:7]
	global_load_dwordx4 v[156:159], v[60:61], off nt
	v_lshl_add_u64 v[60:61], v[60:61], 0, s[6:7]
	global_load_dwordx4 v[160:163], v[60:61], off nt
	v_lshl_add_u64 v[60:61], v[60:61], 0, s[6:7]
	global_load_dwordx4 v[164:167], v[60:61], off nt
	v_lshl_add_u64 v[60:61], v[60:61], 0, s[6:7]
	global_load_dwordx4 v[8:11], v[60:61], off nt
	v_lshl_add_u64 v[60:61], v[60:61], 0, s[6:7]
	global_load_dwordx4 v[12:15], v[60:61], off nt
	v_lshl_add_u64 v[60:61], v[60:61], 0, s[6:7]
	global_load_dwordx4 v[16:19], v[60:61], off nt
	v_lshl_add_u64 v[60:61], v[60:61], 0, s[6:7]
	global_load_dwordx4 v[40:43], v[60:61], off nt
	v_lshl_add_u64 v[60:61], v[60:61], 0, s[6:7]
	global_load_dwordx4 v[48:51], v[60:61], off nt
	v_lshl_add_u64 v[60:61], v[60:61], 0, s[6:7]
	global_load_dwordx4 v[56:59], v[60:61], off nt
	v_lshl_add_u64 v[60:61], v[60:61], 0, s[6:7]
	v_mov_b32_e32 v34, 0
	v_mov_b32_e32 v35, 0
	v_mov_b32_e32 v36, 0
	v_mov_b32_e32 v37, 0
	v_mov_b32_e32 v30, 0
	v_mov_b32_e32 v31, 0
	v_mov_b32_e32 v32, 0
	v_mov_b32_e32 v33, 0
	v_mov_b32_e32 v26, 0
	v_mov_b32_e32 v27, 0
	v_mov_b32_e32 v28, 0
	v_mov_b32_e32 v29, 0
	s_waitcnt vmcnt(32)
	v_mul_f32_e32 v20, 0xbfb8aa3b, v2
	v_mul_f32_e32 v21, 0xbfb8aa3b, v3
	v_mul_f32_e32 v25, 0xbfb8aa3b, v4
	v_exp_f32_e32 v20, v20
	v_exp_f32_e32 v21, v21
	v_exp_f32_e32 v25, v25
	s_nop 0
	v_add_f32_e32 v20, 1.0, v20
	v_add_f32_e32 v21, 1.0, v21
	v_add_f32_e32 v25, 1.0, v25
	v_div_scale_f32 v38, s[8:9], v20, v20, v2
	v_div_scale_f32 v39, s[10:11], v21, v21, v3
	v_div_scale_f32 v44, s[12:13], v25, v25, v4
	v_rcp_f32_e32 v45, v38
	v_rcp_f32_e32 v46, v39
	v_rcp_f32_e32 v47, v44
	s_nop 0
	v_fma_f32 v52, -v38, v45, 1.0
	v_fma_f32 v53, -v39, v46, 1.0
	v_fma_f32 v62, -v44, v47, 1.0
	v_fmac_f32_e32 v45, v52, v45
	v_fmac_f32_e32 v46, v53, v46
	v_fmac_f32_e32 v47, v62, v47
	v_div_scale_f32 v63, vcc, v2, v20, v2
	v_mul_f32_e32 v7, v63, v45
	v_fma_f32 v52, -v38, v7, v63
	v_fmac_f32_e32 v7, v52, v45
	v_fma_f32 v38, -v38, v7, v63
	s_nop 0
	v_div_fmas_f32 v7, v38, v45, v7
	v_div_fixup_f32 v22, v7, v20, v2
	v_div_scale_f32 v168, vcc, v3, v21, v3
	v_mul_f32_e32 v5, v168, v46
	v_fma_f32 v53, -v39, v5, v168
	v_fmac_f32_e32 v5, v53, v46
	v_fma_f32 v39, -v39, v5, v168
	s_nop 0
	v_div_fmas_f32 v5, v39, v46, v5
	v_div_fixup_f32 v23, v5, v21, v3
	v_div_scale_f32 v169, vcc, v4, v25, v4
	v_mul_f32_e32 v6, v169, v47
	v_fma_f32 v62, -v44, v6, v169
	v_fmac_f32_e32 v6, v62, v47
	v_fma_f32 v44, -v44, v6, v169
	s_nop 0
	v_div_fmas_f32 v6, v44, v47, v6
	v_div_fixup_f32 v24, v6, v25, v4
	s_waitcnt vmcnt(16)
; #define GAS __attribute__((address_space(1)))
; __device__ __forceinline__ float silu_f(float v) { return v / (1.f + __expf(-v)); }
; __device__ __forceinline__ void p0_prologue(Frame& F) {
;     ...
;             for (int k = kbeg; k < kbeg + DM / ADA_KS; ++k) {
;                 const f32x4 w = *(const GAS f32x4*)(W + (size_t)k * 6144);
;                 const float s0 = silu_f(c[k]), s1 = silu_f(c[DM + k]), s2 = silu_f(cctx[k]);
;                 a0 += w * s0; a1 += w * s1; a2 += w * s2;
	v_readlane_b32 s8, v22, 0
	v_readlane_b32 s9, v23, 0
	v_readlane_b32 s10, v24, 0
	v_fma_f32 v34, v64, s8, v34
	v_fma_f32 v35, v65, s8, v35
	v_fma_f32 v36, v66, s8, v36
	v_fma_f32 v37, v67, s8, v37
	v_fma_f32 v30, v64, s9, v30
	v_fma_f32 v31, v65, s9, v31
	v_fma_f32 v32, v66, s9, v32
	v_fma_f32 v33, v67, s9, v33
	v_fma_f32 v26, v64, s10, v26
	v_fma_f32 v27, v65, s10, v27
	v_fma_f32 v28, v66, s10, v28
	v_fma_f32 v29, v67, s10, v29
	v_readlane_b32 s8, v22, 1
	v_readlane_b32 s9, v23, 1
	v_readlane_b32 s10, v24, 1
	v_fma_f32 v34, v68, s8, v34
	v_fma_f32 v35, v69, s8, v35
	v_fma_f32 v36, v70, s8, v36
	v_fma_f32 v37, v71, s8, v37
	v_fma_f32 v30, v68, s9, v30
	v_fma_f32 v31, v69, s9, v31
	v_fma_f32 v32, v70, s9, v32
	v_fma_f32 v33, v71, s9, v33
	v_fma_f32 v26, v68, s10, v26
	v_fma_f32 v27, v69, s10, v27
	v_fma_f32 v28, v70, s10, v28
	v_fma_f32 v29, v71, s10, v29
	v_readlane_b32 s8, v22, 2
	v_readlane_b32 s9, v23, 2
	v_readlane_b32 s10, v24, 2
	v_fma_f32 v34, v72, s8, v34
	v_fma_f32 v35, v73, s8, v35
	v_fma_f32 v36, v74, s8, v36
	v_fma_f32 v37, v75, s8, v37
	v_fma_f32 v30, v72, s9, v30
	v_fma_f32 v31, v73, s9, v31
	v_fma_f32 v32, v74, s9, v32
	v_fma_f32 v33, v75, s9, v33
	v_fma_f32 v26, v72, s10, v26
	v_fma_f32 v27, v73, s10, v27
	v_fma_f32 v28, v74, s10, v28
	v_fma_f32 v29, v75, s10, v29
	v_readlane_b32 s8, v22, 3
	v_readlane_b32 s9, v23, 3
	v_readlane_b32 s10, v24, 3
	v_fma_f32 v34, v76, s8, v34
	v_fma_f32 v35, v77, s8, v35
	v_fma_f32 v36, v78, s8, v36
	v_fma_f32 v37, v79, s8, v37
	v_fma_f32 v30, v76, s9, v30
	v_fma_f32 v31, v77, s9, v31
	v_fma_f32 v32, v78, s9, v32
	v_fma_f32 v33, v79, s9, v33
	v_fma_f32 v26, v76, s10, v26
	v_fma_f32 v27, v77, s10, v27
	v_fma_f32 v28, v78, s10, v28
	v_fma_f32 v29, v79, s10, v29
	v_readlane_b32 s8, v22, 4
	v_readlane_b32 s9, v23, 4
	v_readlane_b32 s10, v24, 4
	v_fma_f32 v34, v80, s8, v34
	v_fma_f32 v35, v81, s8, v35
	v_fma_f32 v36, v82, s8, v36
	v_fma_f32 v37, v83, s8, v37
	v_fma_f32 v30, v80, s9, v30
	v_fma_f32 v31, v81, s9, v31
	v_fma_f32 v32, v82, s9, v32
	v_fma_f32 v33, v83, s9, v33
	v_fma_f32 v26, v80, s10, v26
	v_fma_f32 v27, v81, s10, v27
	v_fma_f32 v28, v82, s10, v28
	v_fma_f32 v29, v83, s10, v29
	v_readlane_b32 s8, v22, 5
	v_readlane_b32 s9, v23, 5
	v_readlane_b32 s10, v24, 5
	v_fma_f32 v34, v84, s8, v34
	v_fma_f32 v35, v85, s8, v35
	v_fma_f32 v36, v86, s8, v36
	v_fma_f32 v37, v87, s8, v37
	v_fma_f32 v30, v84, s9, v30
	v_fma_f32 v31, v85, s9, v31
	v_fma_f32 v32, v86, s9, v32
	v_fma_f32 v33, v87, s9, v33
	v_fma_f32 v26, v84, s10, v26
	v_fma_f32 v27, v85, s10, v27
	v_fma_f32 v28, v86, s10, v28
	v_fma_f32 v29, v87, s10, v29
	v_readlane_b32 s8, v22, 6
	v_readlane_b32 s9, v23, 6
	v_readlane_b32 s10, v24, 6
	v_fma_f32 v34, v88, s8, v34
	v_fma_f32 v35, v89, s8, v35
	v_fma_f32 v36, v90, s8, v36
	v_fma_f32 v37, v91, s8, v37
	v_fma_f32 v30, v88, s9, v30
	v_fma_f32 v31, v89, s9, v31
	v_fma_f32 v32, v90, s9, v32
	v_fma_f32 v33, v91, s9, v33
	v_fma_f32 v26, v88, s10, v26
	v_fma_f32 v27, v89, s10, v27
	v_fma_f32 v28, v90, s10, v28
	v_fma_f32 v29, v91, s10, v29
	v_readlane_b32 s8, v22, 7
	v_readlane_b32 s9, v23, 7
	v_readlane_b32 s10, v24, 7
	v_fma_f32 v34, v92, s8, v34
	v_fma_f32 v35, v93, s8, v35
	v_fma_f32 v36, v94, s8, v36
	v_fma_f32 v37, v95, s8, v37
	v_fma_f32 v30, v92, s9, v30
	v_fma_f32 v31, v93, s9, v31
	v_fma_f32 v32, v94, s9, v32
	v_fma_f32 v33, v95, s9, v33
	v_fma_f32 v26, v92, s10, v26
	v_fma_f32 v27, v93, s10, v27
	v_fma_f32 v28, v94, s10, v28
	v_fma_f32 v29, v95, s10, v29
	v_readlane_b32 s8, v22, 8
	v_readlane_b32 s9, v23, 8
	v_readlane_b32 s10, v24, 8
	v_fma_f32 v34, v96, s8, v34
	v_fma_f32 v35, v97, s8, v35
	v_fma_f32 v36, v98, s8, v36
	v_fma_f32 v37, v99, s8, v37
	v_fma_f32 v30, v96, s9, v30
	v_fma_f32 v31, v97, s9, v31
	v_fma_f32 v32, v98, s9, v32
	v_fma_f32 v33, v99, s9, v33
	v_fma_f32 v26, v96, s10, v26
	v_fma_f32 v27, v97, s10, v27
	v_fma_f32 v28, v98, s10, v28
	v_fma_f32 v29, v99, s10, v29
	v_readlane_b32 s8, v22, 9
	v_readlane_b32 s9, v23, 9
	v_readlane_b32 s10, v24, 9
	v_fma_f32 v34, v100, s8, v34
	v_fma_f32 v35, v101, s8, v35
	v_fma_f32 v36, v102, s8, v36
	v_fma_f32 v37, v103, s8, v37
	v_fma_f32 v30, v100, s9, v30
	v_fma_f32 v31, v101, s9, v31
	v_fma_f32 v32, v102, s9, v32
	v_fma_f32 v33, v103, s9, v33
	v_fma_f32 v26, v100, s10, v26
	v_fma_f32 v27, v101, s10, v27
	v_fma_f32 v28, v102, s10, v28
	v_fma_f32 v29, v103, s10, v29
	v_readlane_b32 s8, v22, 10
	v_readlane_b32 s9, v23, 10
	v_readlane_b32 s10, v24, 10
	v_fma_f32 v34, v104, s8, v34
	v_fma_f32 v35, v105, s8, v35
	v_fma_f32 v36, v106, s8, v36
	v_fma_f32 v37, v107, s8, v37
	v_fma_f32 v30, v104, s9, v30
	v_fma_f32 v31, v105, s9, v31
	v_fma_f32 v32, v106, s9, v32
	v_fma_f32 v33, v107, s9, v33
	v_fma_f32 v26, v104, s10, v26
	v_fma_f32 v27, v105, s10, v27
	v_fma_f32 v28, v106, s10, v28
	v_fma_f32 v29, v107, s10, v29
	v_readlane_b32 s8, v22, 11
	v_readlane_b32 s9, v23, 11
	v_readlane_b32 s10, v24, 11
	v_fma_f32 v34, v108, s8, v34
	v_fma_f32 v35, v109, s8, v35
	v_fma_f32 v36, v110, s8, v36
	v_fma_f32 v37, v111, s8, v37
	v_fma_f32 v30, v108, s9, v30
	v_fma_f32 v31, v109, s9, v31
	v_fma_f32 v32, v110, s9, v32
	v_fma_f32 v33, v111, s9, v33
	v_fma_f32 v26, v108, s10, v26
	v_fma_f32 v27, v109, s10, v27
	v_fma_f32 v28, v110, s10, v28
	v_fma_f32 v29, v111, s10, v29
	v_readlane_b32 s8, v22, 12
	v_readlane_b32 s9, v23, 12
	v_readlane_b32 s10, v24, 12
	v_fma_f32 v34, v112, s8, v34
	v_fma_f32 v35, v113, s8, v35
	v_fma_f32 v36, v114, s8, v36
	v_fma_f32 v37, v115, s8, v37
	v_fma_f32 v30, v112, s9, v30
	v_fma_f32 v31, v113, s9, v31
	v_fma_f32 v32, v114, s9, v32
	v_fma_f32 v33, v115, s9, v33
	v_fma_f32 v26, v112, s10, v26
	v_fma_f32 v27, v113, s10, v27
; #define GAS __attribute__((address_space(1)))
; __device__ __forceinline__ float silu_f(float v) { return v / (1.f + __expf(-v)); }
; __device__ __forceinline__ void p0_prologue(Frame& F) {
;     ...
;             for (int k = kbeg; k < kbeg + DM / ADA_KS; ++k) {
;                 const f32x4 w = *(const GAS f32x4*)(W + (size_t)k * 6144);
;                 const float s0 = silu_f(c[k]), s1 = silu_f(c[DM + k]), s2 = silu_f(cctx[k]);
;                 a0 += w * s0; a1 += w * s1; a2 += w * s2;
	v_fma_f32 v28, v114, s10, v28
	v_fma_f32 v29, v115, s10, v29
	v_readlane_b32 s8, v22, 13
	v_readlane_b32 s9, v23, 13
	v_readlane_b32 s10, v24, 13
	v_fma_f32 v34, v116, s8, v34
	v_fma_f32 v35, v117, s8, v35
	v_fma_f32 v36, v118, s8, v36
	v_fma_f32 v37, v119, s8, v37
	v_fma_f32 v30, v116, s9, v30
	v_fma_f32 v31, v117, s9, v31
	v_fma_f32 v32, v118, s9, v32
	v_fma_f32 v33, v119, s9, v33
	v_fma_f32 v26, v116, s10, v26
	v_fma_f32 v27, v117, s10, v27
	v_fma_f32 v28, v118, s10, v28
	v_fma_f32 v29, v119, s10, v29
	v_readlane_b32 s8, v22, 14
	v_readlane_b32 s9, v23, 14
	v_readlane_b32 s10, v24, 14
	v_fma_f32 v34, v120, s8, v34
	v_fma_f32 v35, v121, s8, v35
	v_fma_f32 v36, v122, s8, v36
	v_fma_f32 v37, v123, s8, v37
	v_fma_f32 v30, v120, s9, v30
	v_fma_f32 v31, v121, s9, v31
	v_fma_f32 v32, v122, s9, v32
	v_fma_f32 v33, v123, s9, v33
	v_fma_f32 v26, v120, s10, v26
	v_fma_f32 v27, v121, s10, v27
	v_fma_f32 v28, v122, s10, v28
	v_fma_f32 v29, v123, s10, v29
	v_readlane_b32 s8, v22, 15
	v_readlane_b32 s9, v23, 15
	v_readlane_b32 s10, v24, 15
	v_fma_f32 v34, v124, s8, v34
	v_fma_f32 v35, v125, s8, v35
	v_fma_f32 v36, v126, s8, v36
	v_fma_f32 v37, v127, s8, v37
	v_fma_f32 v30, v124, s9, v30
	v_fma_f32 v31, v125, s9, v31
	v_fma_f32 v32, v126, s9, v32
	v_fma_f32 v33, v127, s9, v33
	v_fma_f32 v26, v124, s10, v26
	v_fma_f32 v27, v125, s10, v27
	v_fma_f32 v28, v126, s10, v28
	v_fma_f32 v29, v127, s10, v29
	global_load_dwordx4 v[64:67], v[60:61], off nt
	v_lshl_add_u64 v[60:61], v[60:61], 0, s[6:7]
	global_load_dwordx4 v[68:71], v[60:61], off nt
	v_lshl_add_u64 v[60:61], v[60:61], 0, s[6:7]
	global_load_dwordx4 v[72:75], v[60:61], off nt
	v_lshl_add_u64 v[60:61], v[60:61], 0, s[6:7]
	global_load_dwordx4 v[76:79], v[60:61], off nt
	v_lshl_add_u64 v[60:61], v[60:61], 0, s[6:7]
	global_load_dwordx4 v[80:83], v[60:61], off nt
	v_lshl_add_u64 v[60:61], v[60:61], 0, s[6:7]
	global_load_dwordx4 v[84:87], v[60:61], off nt
	v_lshl_add_u64 v[60:61], v[60:61], 0, s[6:7]
	global_load_dwordx4 v[88:91], v[60:61], off nt
	v_lshl_add_u64 v[60:61], v[60:61], 0, s[6:7]
	global_load_dwordx4 v[92:95], v[60:61], off nt
	v_lshl_add_u64 v[60:61], v[60:61], 0, s[6:7]
	global_load_dwordx4 v[96:99], v[60:61], off nt
	v_lshl_add_u64 v[60:61], v[60:61], 0, s[6:7]
	global_load_dwordx4 v[100:103], v[60:61], off nt
	v_lshl_add_u64 v[60:61], v[60:61], 0, s[6:7]
	global_load_dwordx4 v[104:107], v[60:61], off nt
	v_lshl_add_u64 v[60:61], v[60:61], 0, s[6:7]
	global_load_dwordx4 v[108:111], v[60:61], off nt
	v_lshl_add_u64 v[60:61], v[60:61], 0, s[6:7]
	global_load_dwordx4 v[112:115], v[60:61], off nt
	v_lshl_add_u64 v[60:61], v[60:61], 0, s[6:7]
	global_load_dwordx4 v[116:119], v[60:61], off nt
	v_lshl_add_u64 v[60:61], v[60:61], 0, s[6:7]
	global_load_dwordx4 v[120:123], v[60:61], off nt
	v_lshl_add_u64 v[60:61], v[60:61], 0, s[6:7]
	global_load_dwordx4 v[124:127], v[60:61], off nt
	v_lshl_add_u64 v[60:61], v[60:61], 0, s[6:7]
	s_waitcnt vmcnt(16)
	v_readlane_b32 s8, v22, 16
	v_readlane_b32 s9, v23, 16
	v_readlane_b32 s10, v24, 16
	v_fma_f32 v34, v128, s8, v34
	v_fma_f32 v35, v129, s8, v35
	v_fma_f32 v36, v130, s8, v36
	v_fma_f32 v37, v131, s8, v37
	v_fma_f32 v30, v128, s9, v30
	v_fma_f32 v31, v129, s9, v31
	v_fma_f32 v32, v130, s9, v32
	v_fma_f32 v33, v131, s9, v33
	v_fma_f32 v26, v128, s10, v26
	v_fma_f32 v27, v129, s10, v27
	v_fma_f32 v28, v130, s10, v28
	v_fma_f32 v29, v131, s10, v29
	v_readlane_b32 s8, v22, 17
	v_readlane_b32 s9, v23, 17
	v_readlane_b32 s10, v24, 17
	v_fma_f32 v34, v132, s8, v34
	v_fma_f32 v35, v133, s8, v35
	v_fma_f32 v36, v134, s8, v36
	v_fma_f32 v37, v135, s8, v37
	v_fma_f32 v30, v132, s9, v30
	v_fma_f32 v31, v133, s9, v31
	v_fma_f32 v32, v134, s9, v32
	v_fma_f32 v33, v135, s9, v33
	v_fma_f32 v26, v132, s10, v26
	v_fma_f32 v27, v133, s10, v27
	v_fma_f32 v28, v134, s10, v28
	v_fma_f32 v29, v135, s10, v29
	v_readlane_b32 s8, v22, 18
	v_readlane_b32 s9, v23, 18
	v_readlane_b32 s10, v24, 18
	v_fma_f32 v34, v136, s8, v34
	v_fma_f32 v35, v137, s8, v35
	v_fma_f32 v36, v138, s8, v36
	v_fma_f32 v37, v139, s8, v37
	v_fma_f32 v30, v136, s9, v30
	v_fma_f32 v31, v137, s9, v31
	v_fma_f32 v32, v138, s9, v32
	v_fma_f32 v33, v139, s9, v33
	v_fma_f32 v26, v136, s10, v26
	v_fma_f32 v27, v137, s10, v27
	v_fma_f32 v28, v138, s10, v28
	v_fma_f32 v29, v139, s10, v29
	v_readlane_b32 s8, v22, 19
	v_readlane_b32 s9, v23, 19
	v_readlane_b32 s10, v24, 19
	v_fma_f32 v34, v140, s8, v34
	v_fma_f32 v35, v141, s8, v35
	v_fma_f32 v36, v142, s8, v36
	v_fma_f32 v37, v143, s8, v37
	v_fma_f32 v30, v140, s9, v30
	v_fma_f32 v31, v141, s9, v31
	v_fma_f32 v32, v142, s9, v32
	v_fma_f32 v33, v143, s9, v33
	v_fma_f32 v26, v140, s10, v26
	v_fma_f32 v27, v141, s10, v27
	v_fma_f32 v28, v142, s10, v28
	v_fma_f32 v29, v143, s10, v29
	v_readlane_b32 s8, v22, 20
	v_readlane_b32 s9, v23, 20
	v_readlane_b32 s10, v24, 20
	v_fma_f32 v34, v144, s8, v34
	v_fma_f32 v35, v145, s8, v35
	v_fma_f32 v36, v146, s8, v36
	v_fma_f32 v37, v147, s8, v37
	v_fma_f32 v30, v144, s9, v30
	v_fma_f32 v31, v145, s9, v31
	v_fma_f32 v32, v146, s9, v32
	v_fma_f32 v33, v147, s9, v33
	v_fma_f32 v26, v144, s10, v26
	v_fma_f32 v27, v145, s10, v27
	v_fma_f32 v28, v146, s10, v28
	v_fma_f32 v29, v147, s10, v29
	v_readlane_b32 s8, v22, 21
	v_readlane_b32 s9, v23, 21
	v_readlane_b32 s10, v24, 21
	v_fma_f32 v34, v148, s8, v34
	v_fma_f32 v35, v149, s8, v35
	v_fma_f32 v36, v150, s8, v36
	v_fma_f32 v37, v151, s8, v37
	v_fma_f32 v30, v148, s9, v30
	v_fma_f32 v31, v149, s9, v31
	v_fma_f32 v32, v150, s9, v32
	v_fma_f32 v33, v151, s9, v33
	v_fma_f32 v26, v148, s10, v26
	v_fma_f32 v27, v149, s10, v27
	v_fma_f32 v28, v150, s10, v28
	v_fma_f32 v29, v151, s10, v29
; #define GAS __attribute__((address_space(1)))
; __device__ __forceinline__ float silu_f(float v) { return v / (1.f + __expf(-v)); }
; __device__ __forceinline__ void p0_prologue(Frame& F) {
;     ...
;             for (int k = kbeg; k < kbeg + DM / ADA_KS; ++k) {
;                 const f32x4 w = *(const GAS f32x4*)(W + (size_t)k * 6144);
;                 const float s0 = silu_f(c[k]), s1 = silu_f(c[DM + k]), s2 = silu_f(cctx[k]);
;                 a0 += w * s0; a1 += w * s1; a2 += w * s2;
	v_readlane_b32 s8, v22, 22
	v_readlane_b32 s9, v23, 22
	v_readlane_b32 s10, v24, 22
	v_fma_f32 v34, v152, s8, v34
	v_fma_f32 v35, v153, s8, v35
	v_fma_f32 v36, v154, s8, v36
	v_fma_f32 v37, v155, s8, v37
	v_fma_f32 v30, v152, s9, v30
	v_fma_f32 v31, v153, s9, v31
	v_fma_f32 v32, v154, s9, v32
	v_fma_f32 v33, v155, s9, v33
	v_fma_f32 v26, v152, s10, v26
	v_fma_f32 v27, v153, s10, v27
	v_fma_f32 v28, v154, s10, v28
	v_fma_f32 v29, v155, s10, v29
	v_readlane_b32 s8, v22, 23
	v_readlane_b32 s9, v23, 23
	v_readlane_b32 s10, v24, 23
	v_fma_f32 v34, v156, s8, v34
	v_fma_f32 v35, v157, s8, v35
	v_fma_f32 v36, v158, s8, v36
	v_fma_f32 v37, v159, s8, v37
	v_fma_f32 v30, v156, s9, v30
	v_fma_f32 v31, v157, s9, v31
	v_fma_f32 v32, v158, s9, v32
	v_fma_f32 v33, v159, s9, v33
	v_fma_f32 v26, v156, s10, v26
	v_fma_f32 v27, v157, s10, v27
	v_fma_f32 v28, v158, s10, v28
	v_fma_f32 v29, v159, s10, v29
	v_readlane_b32 s8, v22, 24
	v_readlane_b32 s9, v23, 24
	v_readlane_b32 s10, v24, 24
	v_fma_f32 v34, v160, s8, v34
	v_fma_f32 v35, v161, s8, v35
	v_fma_f32 v36, v162, s8, v36
	v_fma_f32 v37, v163, s8, v37
	v_fma_f32 v30, v160, s9, v30
	v_fma_f32 v31, v161, s9, v31
	v_fma_f32 v32, v162, s9, v32
	v_fma_f32 v33, v163, s9, v33
	v_fma_f32 v26, v160, s10, v26
	v_fma_f32 v27, v161, s10, v27
	v_fma_f32 v28, v162, s10, v28
	v_fma_f32 v29, v163, s10, v29
	v_readlane_b32 s8, v22, 25
	v_readlane_b32 s9, v23, 25
	v_readlane_b32 s10, v24, 25
	v_fma_f32 v34, v164, s8, v34
	v_fma_f32 v35, v165, s8, v35
	v_fma_f32 v36, v166, s8, v36
	v_fma_f32 v37, v167, s8, v37
	v_fma_f32 v30, v164, s9, v30
	v_fma_f32 v31, v165, s9, v31
	v_fma_f32 v32, v166, s9, v32
	v_fma_f32 v33, v167, s9, v33
	v_fma_f32 v26, v164, s10, v26
	v_fma_f32 v27, v165, s10, v27
	v_fma_f32 v28, v166, s10, v28
	v_fma_f32 v29, v167, s10, v29
	v_readlane_b32 s8, v22, 26
	v_readlane_b32 s9, v23, 26
	v_readlane_b32 s10, v24, 26
	v_fma_f32 v34, v8, s8, v34
	v_fma_f32 v35, v9, s8, v35
	v_fma_f32 v36, v10, s8, v36
	v_fma_f32 v37, v11, s8, v37
	v_fma_f32 v30, v8, s9, v30
	v_fma_f32 v31, v9, s9, v31
	v_fma_f32 v32, v10, s9, v32
	v_fma_f32 v33, v11, s9, v33
	v_fma_f32 v26, v8, s10, v26
	v_fma_f32 v27, v9, s10, v27
	v_fma_f32 v28, v10, s10, v28
	v_fma_f32 v29, v11, s10, v29
	v_readlane_b32 s8, v22, 27
	v_readlane_b32 s9, v23, 27
	v_readlane_b32 s10, v24, 27
	v_fma_f32 v34, v12, s8, v34
	v_fma_f32 v35, v13, s8, v35
	v_fma_f32 v36, v14, s8, v36
	v_fma_f32 v37, v15, s8, v37
	v_fma_f32 v30, v12, s9, v30
	v_fma_f32 v31, v13, s9, v31
	v_fma_f32 v32, v14, s9, v32
	v_fma_f32 v33, v15, s9, v33
	v_fma_f32 v26, v12, s10, v26
	v_fma_f32 v27, v13, s10, v27
	v_fma_f32 v28, v14, s10, v28
	v_fma_f32 v29, v15, s10, v29
	v_readlane_b32 s8, v22, 28
	v_readlane_b32 s9, v23, 28
	v_readlane_b32 s10, v24, 28
	v_fma_f32 v34, v16, s8, v34
	v_fma_f32 v35, v17, s8, v35
	v_fma_f32 v36, v18, s8, v36
	v_fma_f32 v37, v19, s8, v37
	v_fma_f32 v30, v16, s9, v30
	v_fma_f32 v31, v17, s9, v31
	v_fma_f32 v32, v18, s9, v32
	v_fma_f32 v33, v19, s9, v33
	v_fma_f32 v26, v16, s10, v26
	v_fma_f32 v27, v17, s10, v27
	v_fma_f32 v28, v18, s10, v28
	v_fma_f32 v29, v19, s10, v29
	v_readlane_b32 s8, v22, 29
	v_readlane_b32 s9, v23, 29
	v_readlane_b32 s10, v24, 29
	v_fma_f32 v34, v40, s8, v34
	v_fma_f32 v35, v41, s8, v35
	v_fma_f32 v36, v42, s8, v36
	v_fma_f32 v37, v43, s8, v37
	v_fma_f32 v30, v40, s9, v30
	v_fma_f32 v31, v41, s9, v31
	v_fma_f32 v32, v42, s9, v32
	v_fma_f32 v33, v43, s9, v33
	v_fma_f32 v26, v40, s10, v26
	v_fma_f32 v27, v41, s10, v27
	v_fma_f32 v28, v42, s10, v28
	v_fma_f32 v29, v43, s10, v29
	v_readlane_b32 s8, v22, 30
	v_readlane_b32 s9, v23, 30
	v_readlane_b32 s10, v24, 30
	v_fma_f32 v34, v48, s8, v34
	v_fma_f32 v35, v49, s8, v35
	v_fma_f32 v36, v50, s8, v36
	v_fma_f32 v37, v51, s8, v37
	v_fma_f32 v30, v48, s9, v30
	v_fma_f32 v31, v49, s9, v31
	v_fma_f32 v32, v50, s9, v32
	v_fma_f32 v33, v51, s9, v33
	v_fma_f32 v26, v48, s10, v26
	v_fma_f32 v27, v49, s10, v27
	v_fma_f32 v28, v50, s10, v28
	v_fma_f32 v29, v51, s10, v29
	v_readlane_b32 s8, v22, 31
	v_readlane_b32 s9, v23, 31
	v_readlane_b32 s10, v24, 31
	v_fma_f32 v34, v56, s8, v34
	v_fma_f32 v35, v57, s8, v35
	v_fma_f32 v36, v58, s8, v36
	v_fma_f32 v37, v59, s8, v37
	v_fma_f32 v30, v56, s9, v30
	v_fma_f32 v31, v57, s9, v31
	v_fma_f32 v32, v58, s9, v32
	v_fma_f32 v33, v59, s9, v33
	v_fma_f32 v26, v56, s10, v26
	v_fma_f32 v27, v57, s10, v27
	v_fma_f32 v28, v58, s10, v28
	v_fma_f32 v29, v59, s10, v29
	global_load_dwordx4 v[128:131], v[60:61], off nt
	v_lshl_add_u64 v[60:61], v[60:61], 0, s[6:7]
	global_load_dwordx4 v[132:135], v[60:61], off nt
	v_lshl_add_u64 v[60:61], v[60:61], 0, s[6:7]
	global_load_dwordx4 v[136:139], v[60:61], off nt
	v_lshl_add_u64 v[60:61], v[60:61], 0, s[6:7]
	global_load_dwordx4 v[140:143], v[60:61], off nt
	v_lshl_add_u64 v[60:61], v[60:61], 0, s[6:7]
	global_load_dwordx4 v[144:147], v[60:61], off nt
	v_lshl_add_u64 v[60:61], v[60:61], 0, s[6:7]
	global_load_dwordx4 v[148:151], v[60:61], off nt
	v_lshl_add_u64 v[60:61], v[60:61], 0, s[6:7]
	global_load_dwordx4 v[152:155], v[60:61], off nt
	v_lshl_add_u64 v[60:61], v[60:61], 0, s[6:7]
	global_load_dwordx4 v[156:159], v[60:61], off nt
	v_lshl_add_u64 v[60:61], v[60:61], 0, s[6:7]
	global_load_dwordx4 v[160:163], v[60:61], off nt
	v_lshl_add_u64 v[60:61], v[60:61], 0, s[6:7]
	global_load_dwordx4 v[164:167], v[60:61], off nt
	v_lshl_add_u64 v[60:61], v[60:61], 0, s[6:7]
	global_load_dwordx4 v[8:11], v[60:61], off nt
	v_lshl_add_u64 v[60:61], v[60:61], 0, s[6:7]
	global_load_dwordx4 v[12:15], v[60:61], off nt
	v_lshl_add_u64 v[60:61], v[60:61], 0, s[6:7]
	global_load_dwordx4 v[16:19], v[60:61], off nt
	v_lshl_add_u64 v[60:61], v[60:61], 0, s[6:7]
	global_load_dwordx4 v[40:43], v[60:61], off nt
	v_lshl_add_u64 v[60:61], v[60:61], 0, s[6:7]
	global_load_dwordx4 v[48:51], v[60:61], off nt
	v_lshl_add_u64 v[60:61], v[60:61], 0, s[6:7]
	global_load_dwordx4 v[56:59], v[60:61], off nt
	v_lshl_add_u64 v[60:61], v[60:61], 0, s[6:7]
	s_waitcnt vmcnt(16)
; #define GAS __attribute__((address_space(1)))
; __device__ __forceinline__ float silu_f(float v) { return v / (1.f + __expf(-v)); }
; __device__ __forceinline__ void p0_prologue(Frame& F) {
;     ...
;             for (int k = kbeg; k < kbeg + DM / ADA_KS; ++k) {
;                 const f32x4 w = *(const GAS f32x4*)(W + (size_t)k * 6144);
;                 const float s0 = silu_f(c[k]), s1 = silu_f(c[DM + k]), s2 = silu_f(cctx[k]);
;                 a0 += w * s0; a1 += w * s1; a2 += w * s2;
	v_readlane_b32 s8, v22, 32
	v_readlane_b32 s9, v23, 32
	v_readlane_b32 s10, v24, 32
	v_fma_f32 v34, v64, s8, v34
	v_fma_f32 v35, v65, s8, v35
	v_fma_f32 v36, v66, s8, v36
	v_fma_f32 v37, v67, s8, v37
	v_fma_f32 v30, v64, s9, v30
	v_fma_f32 v31, v65, s9, v31
	v_fma_f32 v32, v66, s9, v32
	v_fma_f32 v33, v67, s9, v33
	v_fma_f32 v26, v64, s10, v26
	v_fma_f32 v27, v65, s10, v27
	v_fma_f32 v28, v66, s10, v28
	v_fma_f32 v29, v67, s10, v29
	v_readlane_b32 s8, v22, 33
	v_readlane_b32 s9, v23, 33
	v_readlane_b32 s10, v24, 33
	v_fma_f32 v34, v68, s8, v34
	v_fma_f32 v35, v69, s8, v35
	v_fma_f32 v36, v70, s8, v36
	v_fma_f32 v37, v71, s8, v37
	v_fma_f32 v30, v68, s9, v30
	v_fma_f32 v31, v69, s9, v31
	v_fma_f32 v32, v70, s9, v32
	v_fma_f32 v33, v71, s9, v33
	v_fma_f32 v26, v68, s10, v26
	v_fma_f32 v27, v69, s10, v27
	v_fma_f32 v28, v70, s10, v28
	v_fma_f32 v29, v71, s10, v29
	v_readlane_b32 s8, v22, 34
	v_readlane_b32 s9, v23, 34
	v_readlane_b32 s10, v24, 34
	v_fma_f32 v34, v72, s8, v34
	v_fma_f32 v35, v73, s8, v35
	v_fma_f32 v36, v74, s8, v36
	v_fma_f32 v37, v75, s8, v37
	v_fma_f32 v30, v72, s9, v30
	v_fma_f32 v31, v73, s9, v31
	v_fma_f32 v32, v74, s9, v32
	v_fma_f32 v33, v75, s9, v33
	v_fma_f32 v26, v72, s10, v26
	v_fma_f32 v27, v73, s10, v27
	v_fma_f32 v28, v74, s10, v28
	v_fma_f32 v29, v75, s10, v29
	v_readlane_b32 s8, v22, 35
	v_readlane_b32 s9, v23, 35
	v_readlane_b32 s10, v24, 35
	v_fma_f32 v34, v76, s8, v34
	v_fma_f32 v35, v77, s8, v35
	v_fma_f32 v36, v78, s8, v36
	v_fma_f32 v37, v79, s8, v37
	v_fma_f32 v30, v76, s9, v30
	v_fma_f32 v31, v77, s9, v31
	v_fma_f32 v32, v78, s9, v32
	v_fma_f32 v33, v79, s9, v33
	v_fma_f32 v26, v76, s10, v26
	v_fma_f32 v27, v77, s10, v27
	v_fma_f32 v28, v78, s10, v28
	v_fma_f32 v29, v79, s10, v29
	v_readlane_b32 s8, v22, 36
	v_readlane_b32 s9, v23, 36
	v_readlane_b32 s10, v24, 36
	v_fma_f32 v34, v80, s8, v34
	v_fma_f32 v35, v81, s8, v35
	v_fma_f32 v36, v82, s8, v36
	v_fma_f32 v37, v83, s8, v37
	v_fma_f32 v30, v80, s9, v30
	v_fma_f32 v31, v81, s9, v31
	v_fma_f32 v32, v82, s9, v32
	v_fma_f32 v33, v83, s9, v33
	v_fma_f32 v26, v80, s10, v26
	v_fma_f32 v27, v81, s10, v27
	v_fma_f32 v28, v82, s10, v28
	v_fma_f32 v29, v83, s10, v29
	v_readlane_b32 s8, v22, 37
	v_readlane_b32 s9, v23, 37
	v_readlane_b32 s10, v24, 37
	v_fma_f32 v34, v84, s8, v34
	v_fma_f32 v35, v85, s8, v35
	v_fma_f32 v36, v86, s8, v36
	v_fma_f32 v37, v87, s8, v37
	v_fma_f32 v30, v84, s9, v30
	v_fma_f32 v31, v85, s9, v31
	v_fma_f32 v32, v86, s9, v32
	v_fma_f32 v33, v87, s9, v33
	v_fma_f32 v26, v84, s10, v26
	v_fma_f32 v27, v85, s10, v27
	v_fma_f32 v28, v86, s10, v28
	v_fma_f32 v29, v87, s10, v29
	v_readlane_b32 s8, v22, 38
	v_readlane_b32 s9, v23, 38
	v_readlane_b32 s10, v24, 38
	v_fma_f32 v34, v88, s8, v34
	v_fma_f32 v35, v89, s8, v35
	v_fma_f32 v36, v90, s8, v36
	v_fma_f32 v37, v91, s8, v37
	v_fma_f32 v30, v88, s9, v30
	v_fma_f32 v31, v89, s9, v31
	v_fma_f32 v32, v90, s9, v32
	v_fma_f32 v33, v91, s9, v33
	v_fma_f32 v26, v88, s10, v26
	v_fma_f32 v27, v89, s10, v27
	v_fma_f32 v28, v90, s10, v28
	v_fma_f32 v29, v91, s10, v29
	v_readlane_b32 s8, v22, 39
	v_readlane_b32 s9, v23, 39
	v_readlane_b32 s10, v24, 39
	v_fma_f32 v34, v92, s8, v34
	v_fma_f32 v35, v93, s8, v35
	v_fma_f32 v36, v94, s8, v36
	v_fma_f32 v37, v95, s8, v37
	v_fma_f32 v30, v92, s9, v30
	v_fma_f32 v31, v93, s9, v31
	v_fma_f32 v32, v94, s9, v32
	v_fma_f32 v33, v95, s9, v33
	v_fma_f32 v26, v92, s10, v26
	v_fma_f32 v27, v93, s10, v27
	v_fma_f32 v28, v94, s10, v28
	v_fma_f32 v29, v95, s10, v29
	v_readlane_b32 s8, v22, 40
	v_readlane_b32 s9, v23, 40
	v_readlane_b32 s10, v24, 40
	v_fma_f32 v34, v96, s8, v34
	v_fma_f32 v35, v97, s8, v35
	v_fma_f32 v36, v98, s8, v36
	v_fma_f32 v37, v99, s8, v37
	v_fma_f32 v30, v96, s9, v30
	v_fma_f32 v31, v97, s9, v31
	v_fma_f32 v32, v98, s9, v32
	v_fma_f32 v33, v99, s9, v33
	v_fma_f32 v26, v96, s10, v26
	v_fma_f32 v27, v97, s10, v27
	v_fma_f32 v28, v98, s10, v28
	v_fma_f32 v29, v99, s10, v29
	v_readlane_b32 s8, v22, 41
	v_readlane_b32 s9, v23, 41
	v_readlane_b32 s10, v24, 41
	v_fma_f32 v34, v100, s8, v34
	v_fma_f32 v35, v101, s8, v35
	v_fma_f32 v36, v102, s8, v36
	v_fma_f32 v37, v103, s8, v37
	v_fma_f32 v30, v100, s9, v30
	v_fma_f32 v31, v101, s9, v31
	v_fma_f32 v32, v102, s9, v32
	v_fma_f32 v33, v103, s9, v33
	v_fma_f32 v26, v100, s10, v26
	v_fma_f32 v27, v101, s10, v27
	v_fma_f32 v28, v102, s10, v28
	v_fma_f32 v29, v103, s10, v29
	v_readlane_b32 s8, v22, 42
	v_readlane_b32 s9, v23, 42
	v_readlane_b32 s10, v24, 42
	v_fma_f32 v34, v104, s8, v34
	v_fma_f32 v35, v105, s8, v35
	v_fma_f32 v36, v106, s8, v36
	v_fma_f32 v37, v107, s8, v37
	v_fma_f32 v30, v104, s9, v30
	v_fma_f32 v31, v105, s9, v31
	v_fma_f32 v32, v106, s9, v32
	v_fma_f32 v33, v107, s9, v33
	v_fma_f32 v26, v104, s10, v26
	v_fma_f32 v27, v105, s10, v27
	v_fma_f32 v28, v106, s10, v28
	v_fma_f32 v29, v107, s10, v29
	v_readlane_b32 s8, v22, 43
	v_readlane_b32 s9, v23, 43
	v_readlane_b32 s10, v24, 43
	v_fma_f32 v34, v108, s8, v34
	v_fma_f32 v35, v109, s8, v35
	v_fma_f32 v36, v110, s8, v36
	v_fma_f32 v37, v111, s8, v37
	v_fma_f32 v30, v108, s9, v30
	v_fma_f32 v31, v109, s9, v31
	v_fma_f32 v32, v110, s9, v32
	v_fma_f32 v33, v111, s9, v33
	v_fma_f32 v26, v108, s10, v26
	v_fma_f32 v27, v109, s10, v27
	v_fma_f32 v28, v110, s10, v28
	v_fma_f32 v29, v111, s10, v29
	v_readlane_b32 s8, v22, 44
	v_readlane_b32 s9, v23, 44
	v_readlane_b32 s10, v24, 44
	v_fma_f32 v34, v112, s8, v34
	v_fma_f32 v35, v113, s8, v35
	v_fma_f32 v36, v114, s8, v36
	v_fma_f32 v37, v115, s8, v37
	v_fma_f32 v30, v112, s9, v30
	v_fma_f32 v31, v113, s9, v31
	v_fma_f32 v32, v114, s9, v32
	v_fma_f32 v33, v115, s9, v33
	v_fma_f32 v26, v112, s10, v26
; #define GAS __attribute__((address_space(1)))
; __device__ __forceinline__ float silu_f(float v) { return v / (1.f + __expf(-v)); }
; __device__ __forceinline__ void p0_prologue(Frame& F) {
;     ...
;             for (int k = kbeg; k < kbeg + DM / ADA_KS; ++k) {
;                 const f32x4 w = *(const GAS f32x4*)(W + (size_t)k * 6144);
;                 const float s0 = silu_f(c[k]), s1 = silu_f(c[DM + k]), s2 = silu_f(cctx[k]);
;                 a0 += w * s0; a1 += w * s1; a2 += w * s2;
	v_fma_f32 v27, v113, s10, v27
	v_fma_f32 v28, v114, s10, v28
	v_fma_f32 v29, v115, s10, v29
	v_readlane_b32 s8, v22, 45
	v_readlane_b32 s9, v23, 45
	v_readlane_b32 s10, v24, 45
	v_fma_f32 v34, v116, s8, v34
	v_fma_f32 v35, v117, s8, v35
	v_fma_f32 v36, v118, s8, v36
	v_fma_f32 v37, v119, s8, v37
	v_fma_f32 v30, v116, s9, v30
	v_fma_f32 v31, v117, s9, v31
	v_fma_f32 v32, v118, s9, v32
	v_fma_f32 v33, v119, s9, v33
	v_fma_f32 v26, v116, s10, v26
	v_fma_f32 v27, v117, s10, v27
	v_fma_f32 v28, v118, s10, v28
	v_fma_f32 v29, v119, s10, v29
	v_readlane_b32 s8, v22, 46
	v_readlane_b32 s9, v23, 46
	v_readlane_b32 s10, v24, 46
	v_fma_f32 v34, v120, s8, v34
	v_fma_f32 v35, v121, s8, v35
	v_fma_f32 v36, v122, s8, v36
	v_fma_f32 v37, v123, s8, v37
	v_fma_f32 v30, v120, s9, v30
	v_fma_f32 v31, v121, s9, v31
	v_fma_f32 v32, v122, s9, v32
	v_fma_f32 v33, v123, s9, v33
	v_fma_f32 v26, v120, s10, v26
	v_fma_f32 v27, v121, s10, v27
	v_fma_f32 v28, v122, s10, v28
	v_fma_f32 v29, v123, s10, v29
	v_readlane_b32 s8, v22, 47
	v_readlane_b32 s9, v23, 47
	v_readlane_b32 s10, v24, 47
	v_fma_f32 v34, v124, s8, v34
	v_fma_f32 v35, v125, s8, v35
	v_fma_f32 v36, v126, s8, v36
	v_fma_f32 v37, v127, s8, v37
	v_fma_f32 v30, v124, s9, v30
	v_fma_f32 v31, v125, s9, v31
	v_fma_f32 v32, v126, s9, v32
	v_fma_f32 v33, v127, s9, v33
	v_fma_f32 v26, v124, s10, v26
	v_fma_f32 v27, v125, s10, v27
	v_fma_f32 v28, v126, s10, v28
	v_fma_f32 v29, v127, s10, v29
	s_waitcnt vmcnt(0)
	v_readlane_b32 s8, v22, 48
	v_readlane_b32 s9, v23, 48
	v_readlane_b32 s10, v24, 48
	v_fma_f32 v34, v128, s8, v34
	v_fma_f32 v35, v129, s8, v35
	v_fma_f32 v36, v130, s8, v36
	v_fma_f32 v37, v131, s8, v37
	v_fma_f32 v30, v128, s9, v30
	v_fma_f32 v31, v129, s9, v31
	v_fma_f32 v32, v130, s9, v32
	v_fma_f32 v33, v131, s9, v33
	v_fma_f32 v26, v128, s10, v26
	v_fma_f32 v27, v129, s10, v27
	v_fma_f32 v28, v130, s10, v28
	v_fma_f32 v29, v131, s10, v29
	v_readlane_b32 s8, v22, 49
	v_readlane_b32 s9, v23, 49
	v_readlane_b32 s10, v24, 49
	v_fma_f32 v34, v132, s8, v34
	v_fma_f32 v35, v133, s8, v35
	v_fma_f32 v36, v134, s8, v36
	v_fma_f32 v37, v135, s8, v37
	v_fma_f32 v30, v132, s9, v30
	v_fma_f32 v31, v133, s9, v31
	v_fma_f32 v32, v134, s9, v32
	v_fma_f32 v33, v135, s9, v33
	v_fma_f32 v26, v132, s10, v26
	v_fma_f32 v27, v133, s10, v27
	v_fma_f32 v28, v134, s10, v28
	v_fma_f32 v29, v135, s10, v29
	v_readlane_b32 s8, v22, 50
	v_readlane_b32 s9, v23, 50
	v_readlane_b32 s10, v24, 50
	v_fma_f32 v34, v136, s8, v34
	v_fma_f32 v35, v137, s8, v35
	v_fma_f32 v36, v138, s8, v36
	v_fma_f32 v37, v139, s8, v37
	v_fma_f32 v30, v136, s9, v30
	v_fma_f32 v31, v137, s9, v31
	v_fma_f32 v32, v138, s9, v32
	v_fma_f32 v33, v139, s9, v33
	v_fma_f32 v26, v136, s10, v26
	v_fma_f32 v27, v137, s10, v27
	v_fma_f32 v28, v138, s10, v28
	v_fma_f32 v29, v139, s10, v29
	v_readlane_b32 s8, v22, 51
	v_readlane_b32 s9, v23, 51
	v_readlane_b32 s10, v24, 51
	v_fma_f32 v34, v140, s8, v34
	v_fma_f32 v35, v141, s8, v35
	v_fma_f32 v36, v142, s8, v36
	v_fma_f32 v37, v143, s8, v37
	v_fma_f32 v30, v140, s9, v30
	v_fma_f32 v31, v141, s9, v31
	v_fma_f32 v32, v142, s9, v32
	v_fma_f32 v33, v143, s9, v33
	v_fma_f32 v26, v140, s10, v26
	v_fma_f32 v27, v141, s10, v27
	v_fma_f32 v28, v142, s10, v28
	v_fma_f32 v29, v143, s10, v29
	v_readlane_b32 s8, v22, 52
	v_readlane_b32 s9, v23, 52
	v_readlane_b32 s10, v24, 52
	v_fma_f32 v34, v144, s8, v34
	v_fma_f32 v35, v145, s8, v35
	v_fma_f32 v36, v146, s8, v36
	v_fma_f32 v37, v147, s8, v37
	v_fma_f32 v30, v144, s9, v30
	v_fma_f32 v31, v145, s9, v31
	v_fma_f32 v32, v146, s9, v32
	v_fma_f32 v33, v147, s9, v33
	v_fma_f32 v26, v144, s10, v26
	v_fma_f32 v27, v145, s10, v27
	v_fma_f32 v28, v146, s10, v28
	v_fma_f32 v29, v147, s10, v29
	v_readlane_b32 s8, v22, 53
	v_readlane_b32 s9, v23, 53
	v_readlane_b32 s10, v24, 53
	v_fma_f32 v34, v148, s8, v34
	v_fma_f32 v35, v149, s8, v35
	v_fma_f32 v36, v150, s8, v36
	v_fma_f32 v37, v151, s8, v37
	v_fma_f32 v30, v148, s9, v30
	v_fma_f32 v31, v149, s9, v31
	v_fma_f32 v32, v150, s9, v32
	v_fma_f32 v33, v151, s9, v33
	v_fma_f32 v26, v148, s10, v26
	v_fma_f32 v27, v149, s10, v27
	v_fma_f32 v28, v150, s10, v28
	v_fma_f32 v29, v151, s10, v29
	v_readlane_b32 s8, v22, 54
	v_readlane_b32 s9, v23, 54
	v_readlane_b32 s10, v24, 54
	v_fma_f32 v34, v152, s8, v34
	v_fma_f32 v35, v153, s8, v35
	v_fma_f32 v36, v154, s8, v36
	v_fma_f32 v37, v155, s8, v37
	v_fma_f32 v30, v152, s9, v30
	v_fma_f32 v31, v153, s9, v31
	v_fma_f32 v32, v154, s9, v32
	v_fma_f32 v33, v155, s9, v33
	v_fma_f32 v26, v152, s10, v26
	v_fma_f32 v27, v153, s10, v27
	v_fma_f32 v28, v154, s10, v28
	v_fma_f32 v29, v155, s10, v29
	v_readlane_b32 s8, v22, 55
; #define GAS __attribute__((address_space(1)))
; __device__ __forceinline__ float silu_f(float v) { return v / (1.f + __expf(-v)); }
; __device__ __forceinline__ void p0_prologue(Frame& F) {
;     ...
;             for (int k = kbeg; k < kbeg + DM / ADA_KS; ++k) {
;                 const f32x4 w = *(const GAS f32x4*)(W + (size_t)k * 6144);
;                 const float s0 = silu_f(c[k]), s1 = silu_f(c[DM + k]), s2 = silu_f(cctx[k]);
;                 a0 += w * s0; a1 += w * s1; a2 += w * s2;
;             }
;             float* P = (float*)(F.ws + WS_MODP) + ((size_t)(ks * 2 + l) * 3) * 6144 + cg * 256 + 4 * F.lane;
;             *(GAS f32x4*)(P) = a0; *(GAS f32x4*)(P + 6144) = a1; *(GAS f32x4*)(P + 2 * 6144) = a2;
	v_readlane_b32 s9, v23, 55
	v_readlane_b32 s10, v24, 55
	v_fma_f32 v34, v156, s8, v34
	v_fma_f32 v35, v157, s8, v35
	v_fma_f32 v36, v158, s8, v36
	v_fma_f32 v37, v159, s8, v37
	v_fma_f32 v30, v156, s9, v30
	v_fma_f32 v31, v157, s9, v31
	v_fma_f32 v32, v158, s9, v32
	v_fma_f32 v33, v159, s9, v33
	v_fma_f32 v26, v156, s10, v26
	v_fma_f32 v27, v157, s10, v27
	v_fma_f32 v28, v158, s10, v28
	v_fma_f32 v29, v159, s10, v29
	v_readlane_b32 s8, v22, 56
	v_readlane_b32 s9, v23, 56
	v_readlane_b32 s10, v24, 56
	v_fma_f32 v34, v160, s8, v34
	v_fma_f32 v35, v161, s8, v35
	v_fma_f32 v36, v162, s8, v36
	v_fma_f32 v37, v163, s8, v37
	v_fma_f32 v30, v160, s9, v30
	v_fma_f32 v31, v161, s9, v31
	v_fma_f32 v32, v162, s9, v32
	v_fma_f32 v33, v163, s9, v33
	v_fma_f32 v26, v160, s10, v26
	v_fma_f32 v27, v161, s10, v27
	v_fma_f32 v28, v162, s10, v28
	v_fma_f32 v29, v163, s10, v29
	v_readlane_b32 s8, v22, 57
	v_readlane_b32 s9, v23, 57
	v_readlane_b32 s10, v24, 57
	v_fma_f32 v34, v164, s8, v34
	v_fma_f32 v35, v165, s8, v35
	v_fma_f32 v36, v166, s8, v36
	v_fma_f32 v37, v167, s8, v37
	v_fma_f32 v30, v164, s9, v30
	v_fma_f32 v31, v165, s9, v31
	v_fma_f32 v32, v166, s9, v32
	v_fma_f32 v33, v167, s9, v33
	v_fma_f32 v26, v164, s10, v26
	v_fma_f32 v27, v165, s10, v27
	v_fma_f32 v28, v166, s10, v28
	v_fma_f32 v29, v167, s10, v29
	v_readlane_b32 s8, v22, 58
	v_readlane_b32 s9, v23, 58
	v_readlane_b32 s10, v24, 58
	v_fma_f32 v34, v8, s8, v34
	v_fma_f32 v35, v9, s8, v35
	v_fma_f32 v36, v10, s8, v36
	v_fma_f32 v37, v11, s8, v37
	v_fma_f32 v30, v8, s9, v30
	v_fma_f32 v31, v9, s9, v31
	v_fma_f32 v32, v10, s9, v32
	v_fma_f32 v33, v11, s9, v33
	v_fma_f32 v26, v8, s10, v26
	v_fma_f32 v27, v9, s10, v27
	v_fma_f32 v28, v10, s10, v28
	v_fma_f32 v29, v11, s10, v29
	v_readlane_b32 s8, v22, 59
	v_readlane_b32 s9, v23, 59
	v_readlane_b32 s10, v24, 59
	v_fma_f32 v34, v12, s8, v34
	v_fma_f32 v35, v13, s8, v35
	v_fma_f32 v36, v14, s8, v36
	v_fma_f32 v37, v15, s8, v37
	v_fma_f32 v30, v12, s9, v30
	v_fma_f32 v31, v13, s9, v31
	v_fma_f32 v32, v14, s9, v32
	v_fma_f32 v33, v15, s9, v33
	v_fma_f32 v26, v12, s10, v26
	v_fma_f32 v27, v13, s10, v27
	v_fma_f32 v28, v14, s10, v28
	v_fma_f32 v29, v15, s10, v29
	v_readlane_b32 s8, v22, 60
	v_readlane_b32 s9, v23, 60
	v_readlane_b32 s10, v24, 60
	v_fma_f32 v34, v16, s8, v34
	v_fma_f32 v35, v17, s8, v35
	v_fma_f32 v36, v18, s8, v36
	v_fma_f32 v37, v19, s8, v37
	v_fma_f32 v30, v16, s9, v30
	v_fma_f32 v31, v17, s9, v31
	v_fma_f32 v32, v18, s9, v32
	v_fma_f32 v33, v19, s9, v33
	v_fma_f32 v26, v16, s10, v26
	v_fma_f32 v27, v17, s10, v27
	v_fma_f32 v28, v18, s10, v28
	v_fma_f32 v29, v19, s10, v29
	v_readlane_b32 s8, v22, 61
	v_readlane_b32 s9, v23, 61
	v_readlane_b32 s10, v24, 61
	v_fma_f32 v34, v40, s8, v34
	v_fma_f32 v35, v41, s8, v35
	v_fma_f32 v36, v42, s8, v36
	v_fma_f32 v37, v43, s8, v37
	v_fma_f32 v30, v40, s9, v30
	v_fma_f32 v31, v41, s9, v31
	v_fma_f32 v32, v42, s9, v32
	v_fma_f32 v33, v43, s9, v33
	v_fma_f32 v26, v40, s10, v26
	v_fma_f32 v27, v41, s10, v27
	v_fma_f32 v28, v42, s10, v28
	v_fma_f32 v29, v43, s10, v29
	v_readlane_b32 s8, v22, 62
	v_readlane_b32 s9, v23, 62
	v_readlane_b32 s10, v24, 62
	v_fma_f32 v34, v48, s8, v34
	v_fma_f32 v35, v49, s8, v35
	v_fma_f32 v36, v50, s8, v36
	v_fma_f32 v37, v51, s8, v37
	v_fma_f32 v30, v48, s9, v30
	v_fma_f32 v31, v49, s9, v31
	v_fma_f32 v32, v50, s9, v32
	v_fma_f32 v33, v51, s9, v33
	v_fma_f32 v26, v48, s10, v26
	v_fma_f32 v27, v49, s10, v27
	v_fma_f32 v28, v50, s10, v28
	v_fma_f32 v29, v51, s10, v29
	v_readlane_b32 s8, v22, 63
	v_readlane_b32 s9, v23, 63
	v_readlane_b32 s10, v24, 63
	v_fma_f32 v34, v56, s8, v34
	v_fma_f32 v35, v57, s8, v35
	v_fma_f32 v36, v58, s8, v36
	v_fma_f32 v37, v59, s8, v37
	v_fma_f32 v30, v56, s9, v30
	v_fma_f32 v31, v57, s9, v31
	v_fma_f32 v32, v58, s9, v32
	v_fma_f32 v33, v59, s9, v33
	v_fma_f32 v26, v56, s10, v26
	v_fma_f32 v27, v57, s10, v27
	v_fma_f32 v28, v58, s10, v28
	v_fma_f32 v29, v59, s10, v29
	s_lshl_b32 s4, s70, 1
	s_add_i32 s4, s4, s69
	s_mul_i32 s5, s4, 3
	s_mul_i32 s4, s4, 0x12000
	s_mul_hi_i32 s5, s5, 0x6000
	s_add_u32 s4, s67, s4
	s_addc_u32 s5, s68, s5
	s_add_u32 s0, s4, s0
	s_addc_u32 s1, s5, s1
	v_lshl_add_u64 v[2:3], s[0:1], 0, v[0:1]
	global_store_dwordx4 v0, v[34:37], s[0:1]
	v_add_co_u32_e32 v4, vcc, 0x6000, v2
	v_readlane_b32 s0, v243, 18
	s_nop 0
	v_addc_co_u32_e32 v5, vcc, 0, v3, vcc
	s_mul_i32 s0, s0, 3
	v_add_co_u32_e32 v2, vcc, 0xc000, v2
	s_add_i32 s66, s66, s0
	s_nop 0
	v_addc_co_u32_e32 v3, vcc, 0, v3, vcc
	s_cmpk_gt_i32 s66, 0x2ff
	global_store_dwordx4 v[4:5], v[30:33], off
	global_store_dwordx4 v[2:3], v[26:29], off
	s_cbranch_scc0 .LBB0_1195
